# stack plus P5 start-of-phase L2 warm-up of the lines the sample-row conv+SiLU pass reads through its dependent load chain (prefetch only)
# speedup vs baseline: 1.0034x; 1.0034x over previous
; #define GAS __attribute__((address_space(1)))
; __device__ __forceinline__ void conv_silu_all(Frame& F, const Args& a) {
;     const bf16* Z0 = WSP(bf16, WS_Z); bf16* QC = WSP(bf16, WS_QC); bf16* KC = WSP(bf16, WS_KC);
;     const float* wc = a.in[I_WCONV]; const float* bc = a.in[I_BCONV]; const float* sconv = a.in[I_SCONV];
;     const int gt = F.vcu * (NWAVES * 64) + F.tid, NT = F.G * NWAVES * 64;
;     for (int it = gt + NP * 256; it < M * 256; it += NT) {
;         const int r = it >> 8, col = (it & 255) * 8;
;         float y[8];
;         { const f32x4 b0 = *(const GAS f32x4*)(bc + col), b1 = *(const GAS f32x4*)(bc + col + 4);
;           y[0] = b0[0]; y[1] = b0[1]; y[2] = b0[2]; y[3] = b0[3]; y[4] = b1[0]; y[5] = b1[1]; y[6] = b1[2]; y[7] = b1[3]; }
;         int t, bsm = 0;
;         if (r < NP) t = r & (SEQ - 1); else { const int s = r - NP; bsm = s >> 2; t = s & 3; }
; #pragma unroll
;         for (int j = 0; j < 4; ++j) {
;             const int tt = t - 3 + j;
;             float x[8]; bool have = true;
;             if (tt >= 0) { const v4u w = *(const GAS v4u*)(Z0 + (size_t)(r - 3 + j) * D + col);
;                 x[0] = bflo(w.x); x[1] = bfhi(w.x); x[2] = bflo(w.y); x[3] = bfhi(w.y); x[4] = bflo(w.z); x[5] = bfhi(w.z); x[6] = bflo(w.w); x[7] = bfhi(w.w); }
;             else if (r >= NP) { const float* sp = sconv + (size_t)(bsm * 3 + (tt + 3)) * D + col; const f32x4 s0 = *(const GAS f32x4*)sp, s1 = *(const GAS f32x4*)(sp + 4);
;                 x[0] = s0[0]; x[1] = s0[1]; x[2] = s0[2]; x[3] = s0[3]; x[4] = s1[0]; x[5] = s1[1]; x[6] = s1[2]; x[7] = s1[3]; }
; __device__ __forceinline__ void mlstm_scalar_table_wg(Frame& F, int bh) {
;     const int lane = F.lane, wave = F.wave, b = bh >> 2, h = bh & 3;
;     const float* GT = WSP(float, WS_GATES); float* SCT = WSP(float, WS_SCT) + (size_t)bh * 32 * 384;
;     LAS float* B63 = (LAS float*)F.lds; LAS float* P63 = B63 + 32; LAS float* MC = B63 + 64; LAS float* M63 = B63 + 96;
;     float as[4], pm[4], bc[4];
; #pragma unroll
;     for (int i = 0; i < 4; ++i) { const int c = 4 * wave + i; const size_t r = (size_t)b * SEQ + (size_t)c * 64 + lane;
;         const float ig = GT[r * 8 + h], lf = GT[r * 8 + 4 + h];
;         float s = lf;
; #pragma unroll
;         for (int o = 1; o < 64; o <<= 1) { const float t = __shfl_up(s, o); if (lane >= o) s += t; }
.LBB0_687:
	s_cmp_lt_i32 s92, 6
	s_cselect_b64 s[4:5], -1, 0
	s_and_b64 s[4:5], s[4:5], s[0:1]
	s_andn2_b64 vcc, exec, s[4:5]
	s_cbranch_vccnz .LBB0_848
	s_cmpk_lg_i32 s96, 0x100
	s_cbranch_scc1 .Lwarm5_skip
	v_readlane_b32 s36, v245, 10
	v_readlane_b32 s40, v245, 20
	v_readlane_b32 s41, v245, 21
	s_add_u32 s38, s34, 0x1ed00000
	s_addc_u32 s39, s35, 0
	s_add_u32 s38, s38, 0x1ffd000
	s_addc_u32 s39, s39, 0
	v_lshl_add_u32 v251, s36, 9, v1
	v_and_b32_e32 v254, 0xff, v251
	v_lshrrev_b32_e32 v251, 8, v251
	v_lshlrev_b32_e32 v252, 12, v251
	v_lshl_add_u32 v252, v254, 4, v252
	v_lshrrev_b32_e32 v253, 2, v251
	v_lshl_add_u32 v253, v253, 1, v253
	v_lshlrev_b32_e32 v253, 13, v253
	v_lshl_add_u32 v253, v254, 5, v253
	global_load_dword v250, v252, s[38:39]
	s_add_u32 s38, s38, 0x1000
	s_addc_u32 s39, s39, 0
	global_load_dword v250, v252, s[38:39]
	s_add_u32 s38, s38, 0x1000
	s_addc_u32 s39, s39, 0
	global_load_dword v250, v252, s[38:39]
	s_add_u32 s38, s38, 0x1000
	s_addc_u32 s39, s39, 0
	global_load_dword v250, v252, s[38:39]
	global_load_dword v250, v253, s[40:41]
	s_add_u32 s40, s40, 0x2000
	s_addc_u32 s41, s41, 0
	global_load_dword v250, v253, s[40:41]
	s_add_u32 s40, s40, 0x2000
	s_addc_u32 s41, s41, 0
	global_load_dword v250, v253, s[40:41]
.Lwarm5_skip:
	v_readlane_b32 s0, v245, 10
	v_mov_b32_e32 v216, v1
	s_cmp_gt_i32 s0, 15
	v_readlane_b32 s1, v245, 11
	s_cbranch_scc1 .LBB0_709
	v_mbcnt_lo_u32_b32 v4, -1, 0
	v_mbcnt_hi_u32_b32 v4, -1, v4
	v_and_b32_e32 v5, 64, v4
	v_add_u32_e32 v6, -1, v4
	v_cmp_lt_i32_e32 vcc, v6, v5
	s_add_u32 s3, s34, 0x2fd00000
	s_addc_u32 s24, s35, 0
	v_cndmask_b32_e32 v6, v6, v4, vcc
	v_lshlrev_b32_e32 v18, 2, v6
	v_add_u32_e32 v6, -2, v4
	v_cmp_lt_i32_e32 vcc, v6, v5
	s_lshl_b32 s26, s97, 2
	s_mov_b32 s27, 0
	v_cndmask_b32_e32 v6, v6, v4, vcc
	v_lshlrev_b32_e32 v19, 2, v6
	v_add_u32_e32 v6, -4, v4
	v_cmp_lt_i32_e32 vcc, v6, v5
	s_lshl_b32 s16, s97, 4
	s_add_i32 s25, s16, 0
	v_cndmask_b32_e32 v6, v6, v4, vcc
	v_lshlrev_b32_e32 v20, 2, v6
	v_add_u32_e32 v6, -8, v4
	v_cmp_lt_i32_e32 vcc, v6, v5
	s_or_b32 s16, s26, 1
	s_mov_b32 s17, s27
	v_cndmask_b32_e32 v6, v6, v4, vcc
	s_lshl_b64 s[20:21], s[26:27], 11
	s_lshl_b64 s[22:23], s[16:17], 11
	s_or_b32 s16, s26, 2
	s_or_b32 s26, s26, 3
	v_lshlrev_b32_e32 v21, 2, v6
	v_add_u32_e32 v6, -16, v4
	v_readlane_b32 s28, v245, 10
	s_lshl_b64 s[40:41], s[26:27], 11
	s_mul_i32 s26, s97, 0x600
	v_cmp_lt_i32_e32 vcc, v6, v5
	v_readlane_b32 s29, v245, 11
	s_mov_b32 s30, s28
	s_lshl_b64 s[38:39], s[16:17], 11
	v_cndmask_b32_e32 v6, v6, v4, vcc
	s_lshl_b64 s[52:53], s[26:27], 2
	s_mul_i32 s29, s30, 0xc000
	v_lshlrev_b32_e32 v22, 2, v6
	v_subrev_u32_e32 v6, 32, v4
	s_mul_hi_i32 s28, s28, 0xc000
	s_add_u32 s54, s34, s29
	v_and_b32_e32 v3, 63, v216
	v_cmp_lt_i32_e32 vcc, v6, v5
	s_addc_u32 s55, s35, s28
	s_add_i32 s28, s26, 0x400
	s_mov_b32 s29, s27
	v_cmp_eq_u32_e64 s[0:1], 63, v3
	v_lshlrev_b32_e32 v10, 5, v3
	v_cmp_eq_u32_e64 s[18:19], 0, v3
	v_cmp_gt_u32_e64 s[6:7], 2, v3
	v_cmp_gt_u32_e64 s[8:9], 4, v3
	v_cmp_gt_u32_e64 s[10:11], 8, v3
	v_cmp_gt_u32_e64 s[12:13], 16, v3
	v_cmp_gt_u32_e64 s[14:15], 32, v3
	v_cndmask_b32_e32 v4, v6, v4, vcc
	v_lshlrev_b32_e32 v3, 2, v3
	s_lshl_b64 s[56:57], s[28:29], 2
	s_addk_i32 s26, 0x200
	v_lshlrev_b32_e32 v23, 2, v4
	v_or_b32_e32 v4, s56, v3
	v_mov_b32_e32 v5, s57
	s_mov_b64 s[28:29], 0x3cb00500
	s_lshl_b64 s[58:59], s[26:27], 2
	v_mov_b32_e32 v2, 0
	v_lshl_add_u64 v[14:15], v[4:5], 0, s[28:29]
	v_or_b32_e32 v4, s58, v3
	v_mov_b32_e32 v5, s59
	v_mov_b32_e32 v11, v2
	v_cmp_eq_u32_e64 s[16:17], 0, v216
	v_or_b32_e32 v12, s52, v3
	v_mov_b32_e32 v13, s53
	v_lshl_add_u64 v[16:17], v[4:5], 0, s[28:29]
	v_mov_b32_e32 v24, 0x3cb00000
	s_mov_b32 s26, s30
	s_branch .LBB0_691
